# input projection tile order: the rope column tile goes to the single-tile workgroups of each row group (column permutation for the 7-column-tile row GEMM)
# speedup vs baseline: 1.0039x; 1.0038x over previous
.LBB0_401:
	s_lshl_b32 s76, s46, 6
	v_readlane_b32 s14, v251, 0
	v_mov_b32_e32 v12, v199
	s_cmp_lt_i32 s14, s76
	s_cselect_b64 s[12:13], -1, 0
	s_cmp_ge_i32 s14, s76
	v_readfirstlane_b32 s33, v12
	s_cbranch_scc1 .LBB0_403
	s_lshl_b32 s14, s46, 2
	v_cvt_f32_u32_e32 v0, s14
	s_lshl_b32 s15, s46, 3
	v_readlane_b32 s23, v250, 13
	s_or_b32 s15, s15, s23
	v_rcp_iflag_f32_e32 v0, v0
	s_sub_i32 s23, 0, s14
	v_readlane_b32 s26, v250, 12
	s_mul_i32 s15, s15, s26
	v_mul_f32_e32 v0, 0x4f7ffffe, v0
	v_cvt_u32_f32_e32 v0, v0
	v_readlane_b32 s26, v250, 7
	s_add_i32 s15, s15, s26
	s_abs_i32 s27, s15
	v_readfirstlane_b32 s28, v0
	s_mul_i32 s23, s23, s28
	s_mul_hi_u32 s23, s28, s23
	s_add_i32 s28, s28, s23
	s_mul_hi_u32 s23, s27, s28
	s_mul_i32 s28, s23, s14
	s_sub_i32 s27, s27, s28
	s_ashr_i32 s26, s15, 31
	s_add_i32 s29, s23, 1
	s_sub_i32 s28, s27, s14
	s_cmp_ge_u32 s27, s14
	s_cselect_b32 s23, s29, s23
	s_cselect_b32 s27, s28, s27
	s_add_i32 s28, s23, 1
	s_cmp_ge_u32 s27, s14
	s_cselect_b32 s23, s28, s23
	s_xor_b32 s23, s23, s26
	s_sub_i32 s23, s23, s26
	s_lshl_b32 s26, s23, 2
	s_sub_i32 s27, 64, s26
	s_min_i32 s27, s27, 4
	s_mul_i32 s23, s23, s14
	s_sext_i32_i16 s14, s27
	v_cvt_f32_i32_e32 v0, s14
	s_sub_i32 s23, s15, s23
	s_sext_i32_i16 s15, s23
	s_waitcnt lgkmcnt(0)
	v_cvt_f32_i32_e32 v1, s15
	v_rcp_iflag_f32_e32 v2, v0
	s_xor_b32 s14, s15, s14
	s_ashr_i32 s14, s14, 30
	s_or_b32 s28, s14, 1
	v_mul_f32_e32 v2, v1, v2
	v_trunc_f32_e32 v2, v2
	v_fma_f32 v1, -v2, v0, v1
	v_cvt_i32_f32_e32 v2, v2
	v_cmp_ge_f32_e64 s[14:15], |v1|, |v0|
	s_and_b64 s[14:15], s[14:15], exec
	s_cselect_b32 s14, s28, 0
	v_readfirstlane_b32 s15, v2
	s_add_i32 s14, s15, s14
	s_sext_i32_i16 s62, s14
	s_mul_i32 s14, s14, s27
	s_sub_i32 s14, s23, s14
	s_sext_i32_i16 s14, s14
	s_add_i32 s36, s26, s14
	s_cmp_eq_u32 s46, 7
	s_cbranch_scc0 .Lipp_p
	s_and_b32 s14, s26, 4
	s_mov_b32 s15, 0x6543012
	s_cmp_eq_u32 s14, 0
	s_cselect_b32 s15, 0x2543610, s15
	s_lshl_b32 s14, s62, 2
	s_lshr_b32 s14, s15, s14
	s_and_b32 s62, s14, 7
.Lipp_p:
.LBB0_403:
	s_andn2_b64 vcc, exec, s[12:13]
	s_cbranch_vccnz .LBB0_567
	v_bfe_i32 v2, v12, 27, 1
	v_lshlrev_b32_e32 v0, 4, v12
	v_lshrrev_b32_e32 v2, 22, v2
	v_add_u32_e32 v2, v0, v2
	v_and_b32_e32 v2, 0xfffffc00, v2
	v_sub_u32_e32 v2, v0, v2
	s_waitcnt lgkmcnt(0)
	v_ashrrev_i32_e32 v1, 31, v12
	v_lshrrev_b32_e32 v3, 4, v2
	v_lshrrev_b32_e32 v1, 26, v1
	v_bitop3_b32 v2, v3, v2, 32 bitop3:0x6c
	v_add_u32_e32 v1, v12, v1
	v_ashrrev_i32_e32 v4, 31, v2
	v_ashrrev_i32_e32 v1, 6, v1
	v_lshrrev_b32_e32 v4, 26, v4
	v_lshlrev_b32_e32 v3, 3, v1
	v_add_u32_e32 v4, v2, v4
	v_and_b32_e32 v3, -16, v3
	v_ashrrev_i32_e32 v5, 6, v4
	v_lshlrev_b32_e32 v1, 5, v1
	v_add_u32_e32 v3, v5, v3
	v_and_b32_e32 v13, 32, v1
	v_and_b32_e32 v1, 0xc0, v4
	v_sub_u32_e32 v1, v2, v1
	v_lshlrev_b32_e32 v2, 1, v3
	v_lshrrev_b32_e32 v4, 2, v3
	v_and_b32_e32 v5, 3, v5
	s_mov_b32 s12, 0x7fffffe0
	v_ashrrev_i16_sdwa v1, v223, sext(v1) dst_sel:DWORD dst_unused:UNUSED_PAD src0_sel:DWORD src1_sel:BYTE_0
	v_and_b32_e32 v2, 24, v2
	v_and_b32_e32 v4, 4, v4
	v_and_or_b32 v5, v3, s12, v5
	v_bfe_i32 v14, v1, 0, 16
	v_or3_b32 v2, v5, v4, v2
	v_add_u32_e32 v1, v13, v14
	v_mul_lo_u32 v15, v3, s11
	v_mul_lo_u32 v2, v2, s2
	v_add_u32_e32 v0, 0x2000, v0
	s_waitcnt vmcnt(0)
	v_add_lshl_u32 v154, v1, v15, 1
	v_add_lshl_u32 v156, v2, v1, 1
	v_ashrrev_i32_e32 v1, 31, v0
	v_lshrrev_b32_e32 v1, 22, v1
	v_add_u32_e32 v1, v0, v1
	v_ashrrev_i32_e32 v1, 10, v1
	v_mul_i32_i24_e32 v2, 0x400, v1
	v_sub_u32_e32 v0, v0, v2
	v_lshrrev_b32_e32 v2, 4, v0
	v_bitop3_b32 v0, v2, v0, 32 bitop3:0x6c
	v_ashrrev_i32_e32 v3, 31, v0
	v_lshrrev_b32_e32 v3, 26, v3
	v_lshlrev_b32_e32 v2, 3, v1
	v_add_u32_e32 v3, v0, v3
	v_and_b32_e32 v2, -16, v2
	v_ashrrev_i32_e32 v4, 6, v3
	s_ashr_i32 s42, s33, 6
	v_add_u32_e32 v2, v4, v2
	v_lshlrev_b32_e32 v1, 5, v1
	v_and_b32_e32 v4, 3, v4
	s_lshl_b32 s95, s2, 9
	v_and_b32_e32 v16, 32, v1
	v_and_b32_e32 v1, 0xc0, v3
	v_and_or_b32 v4, v2, s12, v4
	s_ashr_i32 s43, s33, 8
	s_lshl_b32 s12, s11, 8
	s_lshl_b32 s23, s2, 8
	s_lshl_b32 s31, s11, 9
	s_lshl_b32 s14, s42, 10
	s_mul_i32 s26, s95, s62
	v_sub_u32_e32 v0, v0, v1
	v_lshlrev_b32_e32 v1, 1, v2
	v_lshrrev_b32_e32 v3, 2, v2
	s_mul_hi_i32 s15, s95, s62
	s_add_u32 s52, s24, s26
	v_ashrrev_i16_sdwa v0, v223, sext(v0) dst_sel:DWORD dst_unused:UNUSED_PAD src0_sel:DWORD src1_sel:BYTE_0
	v_and_b32_e32 v1, 24, v1
	v_and_b32_e32 v3, 4, v3
	s_addc_u32 s53, s25, s15
	s_add_i32 s15, s14, 0
	v_bfe_i32 v17, v0, 0, 16
	v_or3_b32 v1, v4, v3, v1
	s_add_i32 m0, s15, 0x10000
	v_add_u32_e32 v0, v16, v17
	v_mul_lo_u32 v1, v1, s2
	global_load_lds_dwordx4 v156, s[52:53]
	s_add_i32 m0, s15, 0x12000
	v_add_lshl_u32 v160, v1, v0, 1
	s_add_u32 s26, s52, s23
	global_load_lds_dwordx4 v160, s[52:53]
	s_addc_u32 s27, s53, 0
	s_add_i32 m0, s15, 0x14000
	s_mul_i32 s28, s31, s36
	global_load_lds_dwordx4 v156, s[26:27]
	s_add_i32 m0, s15, 0x16000
	v_mul_lo_u32 v18, v2, s11
	s_mul_hi_i32 s11, s31, s36
	s_add_u32 s54, s96, s28
	v_mov_b32_e32 v157, v197
	v_mov_b32_e32 v161, v197
	s_addc_u32 s55, s97, s11
	s_add_i32 s59, s15, 0x2000
	v_lshl_add_u64 v[4:5], s[26:27], 0, v[156:157]
	v_lshl_add_u64 v[6:7], s[26:27], 0, v[160:161]
	global_load_lds_dwordx4 v160, s[26:27]
	s_mov_b32 m0, s15
	s_add_u32 s26, s54, s12
	v_add_lshl_u32 v158, v0, v18, 1
	global_load_lds_dwordx4 v154, s[54:55]
	s_mov_b32 m0, s59
	s_addc_u32 s27, s55, 0
	s_add_i32 s28, s15, 0x4000
	global_load_lds_dwordx4 v158, s[54:55]
	s_mov_b32 m0, s28
	s_add_i32 s29, s15, 0x6000
	global_load_lds_dwordx4 v154, s[26:27]
	s_mov_b32 m0, s29
	v_mov_b32_e32 v155, v197
	global_load_lds_dwordx4 v158, s[26:27]
	v_mov_b32_e32 v159, v197
	s_cmp_eq_u32 s43, 1
	v_writelane_b32 v249, s44, 62
	s_mov_b32 s13, s37
	v_lshl_add_u64 v[0:1], s[52:53], 0, v[156:157]
	v_lshl_add_u64 v[2:3], s[52:53], 0, v[160:161]
	v_lshl_add_u64 v[8:9], s[54:55], 0, v[154:155]
	v_lshl_add_u64 v[10:11], s[54:55], 0, v[158:159]
	s_cselect_b64 s[26:27], -1, 0
	s_cmp_lg_u32 s43, 1
	v_writelane_b32 v249, s26, 63
	s_nop 1
	v_writelane_b32 v248, s27, 0
	s_cbranch_scc1 .LBB0_406
	s_barrier

.LBB0_409:
	v_readlane_b32 s48, v251, 1
	s_add_i32 s33, s33, 1
	v_readlane_b32 s8, v251, 22
	v_readlane_b32 s50, v251, 3
	s_mul_i32 s8, s33, s8
	s_mul_hi_u32 s9, s33, s50
	s_add_i32 s9, s9, s8
	s_mul_i32 s8, s33, s50
	v_readlane_b32 s48, v251, 0
	s_add_u32 s8, s8, s48
	v_readlane_b32 s48, v251, 21
	s_addc_u32 s9, s9, s48
	v_mov_b64_e32 v[0:1], s[76:77]
	v_readlane_b32 s51, v251, 4
	v_cmp_ge_i64_e32 vcc, s[8:9], v[0:1]
	v_cmp_lt_i64_e64 s[50:51], s[8:9], v[0:1]
	v_readlane_b32 s49, v251, 2
	s_cbranch_vccnz .LBB0_411
	s_ashr_i32 s9, s8, 31
	s_lshr_b32 s9, s9, 29
	s_add_i32 s9, s8, s9
	s_ashr_i32 s13, s9, 3
	s_and_b32 s9, s9, -8
	s_sub_i32 s8, s8, s9
	s_lshr_b32 s9, s8, 31
	s_or_b32 s9, s2, s9
	s_mul_i32 s8, s9, s8
	s_add_i32 s8, s8, s13
	s_abs_i32 s13, s8
	s_mul_hi_u32 s48, s13, s94
	s_mul_i32 s49, s48, s93
	s_sub_i32 s13, s13, s49
	s_ashr_i32 s9, s8, 31
	s_add_i32 s49, s48, 1
	s_sub_i32 s56, s13, s93
	s_cmp_ge_u32 s13, s93
	s_cselect_b32 s48, s49, s48
	s_cselect_b32 s13, s56, s13
	s_add_i32 s49, s48, 1
	s_cmp_ge_u32 s13, s93
	s_cselect_b32 s13, s49, s48
	s_xor_b32 s13, s13, s9
	s_sub_i32 s9, s13, s9
	s_lshl_b32 s48, s9, 2
	s_mul_i32 s9, s9, s93
	s_sub_i32 s8, s8, s9
	s_lshr_b32 s13, s8, 2
	s_and_b32 s8, s8, 3
	s_add_i32 s78, s8, s48
	s_cmp_eq_u32 s93, 28
	s_cbranch_scc0 .Lipp_h
	s_and_b32 s8, s48, 4
	s_mov_b32 s9, 0x6543012
	s_cmp_eq_u32 s8, 0
	s_cselect_b32 s9, 0x2543610, s9
	s_lshl_b32 s8, s13, 2
	s_lshr_b32 s8, s9, s8
	s_and_b32 s13, s8, 7
.Lipp_h:
.LBB0_411:
	v_cndmask_b32_e64 v0, 0, 1, s[50:51]
	v_cmp_ne_u32_e64 s[48:49], 1, v0
	s_andn2_b64 vcc, exec, s[50:51]
	s_mov_b64 s[8:9], s[54:55]
	s_cbranch_vccnz .LBB0_413
	s_mul_i32 s8, s31, s78
	s_mul_hi_i32 s9, s31, s78
	s_add_u32 s8, s96, s8
	s_addc_u32 s9, s97, s9
